# SSD sample loop: last four steps of the 64-lane sum(y^2) butterfly via DPP adds (row_ror / quad_perm) instead of ds_bpermute round trips
# speedup vs baseline: 1.0118x; 1.0031x over previous
.LBB0_300:
	v_add_u32_e32 v69, s18, v61
	ds_read_b32 v70, v69
	v_mov_b32_e32 v91, s19
	ds_read_b32 v71, v91
	ds_read_b32 v90, v91 offset:32
	s_add_i32 s19, s19, 8
	s_addk_i32 s18, 0x200
	s_cmpk_eq_i32 s18, 0x800
	s_waitcnt lgkmcnt(1)
	v_mul_f32_e32 v92, v70, v71
	ds_read_b128 v[70:73], v68
	ds_read_b128 v[74:77], v68 offset:16
	ds_read_b128 v[78:81], v68 offset:32
	ds_read_b128 v[82:85], v68 offset:48
	ds_read_b128 v[86:89], v68 offset:4096
	s_waitcnt lgkmcnt(4)
	v_pk_mul_f32 v[70:71], v[92:93], v[70:71] op_sel_hi:[0,1]
	v_pk_fma_f32 v[94:95], v[30:31], v[90:91], v[70:71] op_sel_hi:[1,0,1]
	s_waitcnt lgkmcnt(0)
	v_fma_f32 v93, v86, v94, 0
	v_fmac_f32_e32 v93, v87, v95
	v_pk_mul_f32 v[30:31], v[92:93], v[72:73] op_sel_hi:[0,1]
	v_pk_fma_f32 v[86:87], v[32:33], v[90:91], v[30:31] op_sel_hi:[1,0,1]
	ds_read_b128 v[30:33], v68 offset:4112
	v_fmac_f32_e32 v93, v88, v86
	v_fmac_f32_e32 v93, v89, v87
	v_pk_mul_f32 v[70:71], v[92:93], v[74:75] op_sel_hi:[0,1]
	v_pk_fma_f32 v[88:89], v[26:27], v[90:91], v[70:71] op_sel_hi:[1,0,1]
	s_waitcnt lgkmcnt(0)
	v_pk_mul_f32 v[26:27], v[30:31], v[88:89]
	s_nop 0
	v_add_f32_e32 v26, v26, v93
	v_add_f32_e32 v30, v27, v26
	v_pk_mul_f32 v[26:27], v[92:93], v[76:77] op_sel_hi:[0,1]
	v_pk_fma_f32 v[96:97], v[28:29], v[90:91], v[26:27] op_sel_hi:[1,0,1]
	s_nop 0
	v_pk_mul_f32 v[26:27], v[32:33], v[96:97]
	s_nop 0
	v_add_f32_e32 v26, v26, v30
	v_add_f32_e32 v32, v27, v26
	ds_read_b128 v[26:29], v68 offset:4128
	v_pk_mul_f32 v[30:31], v[92:93], v[78:79] op_sel_hi:[0,1]
	v_pk_fma_f32 v[78:79], v[22:23], v[90:91], v[30:31] op_sel_hi:[1,0,1]
	s_waitcnt lgkmcnt(0)
	v_pk_mul_f32 v[22:23], v[26:27], v[78:79]
	s_nop 0
	v_add_f32_e32 v22, v22, v32
	v_add_f32_e32 v26, v23, v22
	v_pk_mul_f32 v[22:23], v[92:93], v[80:81] op_sel_hi:[0,1]
	v_pk_fma_f32 v[80:81], v[24:25], v[90:91], v[22:23] op_sel_hi:[1,0,1]
	s_nop 0
	v_pk_mul_f32 v[22:23], v[28:29], v[80:81]
	s_nop 0
	v_add_f32_e32 v22, v22, v26
	v_add_f32_e32 v28, v23, v22
	ds_read_b128 v[22:25], v68 offset:4144
	v_pk_mul_f32 v[26:27], v[92:93], v[82:83] op_sel_hi:[0,1]
	v_pk_fma_f32 v[82:83], v[18:19], v[90:91], v[26:27] op_sel_hi:[1,0,1]
	s_waitcnt lgkmcnt(0)
	v_pk_mul_f32 v[18:19], v[22:23], v[82:83]
	s_nop 0
	v_add_f32_e32 v18, v18, v28
	v_add_f32_e32 v22, v19, v18
	v_pk_mul_f32 v[18:19], v[92:93], v[84:85] op_sel_hi:[0,1]
	v_pk_fma_f32 v[84:85], v[20:21], v[90:91], v[18:19] op_sel_hi:[1,0,1]
	s_nop 0
	v_pk_mul_f32 v[18:19], v[24:25], v[84:85]
	s_nop 0
	v_add_f32_e32 v18, v18, v22
	v_add_f32_e32 v18, v19, v18
	ds_write_b32 v37, v18
	ds_read_b32 v18, v69 offset:256
	ds_read_b32 v19, v91 offset:4
	ds_read_b32 v90, v91 offset:36
	s_waitcnt lgkmcnt(1)
	v_mul_f32_e32 v92, v18, v19
	ds_read_b128 v[18:21], v68 offset:512
	ds_read_b128 v[22:25], v68 offset:528
	ds_read_b128 v[70:73], v68 offset:544
	ds_read_b128 v[74:77], v68 offset:560
	ds_read_b128 v[26:29], v68 offset:4608
	s_waitcnt lgkmcnt(4)
	v_pk_mul_f32 v[18:19], v[92:93], v[18:19] op_sel_hi:[0,1]
	v_pk_fma_f32 v[30:31], v[94:95], v[90:91], v[18:19] op_sel_hi:[1,0,1]
	v_pk_mul_f32 v[18:19], v[92:93], v[20:21] op_sel_hi:[0,1]
	v_pk_fma_f32 v[32:33], v[86:87], v[90:91], v[18:19] op_sel_hi:[1,0,1]
	ds_read_b128 v[18:21], v68 offset:4624
	s_waitcnt lgkmcnt(1)
	v_fma_f32 v69, v26, v30, 0
	v_fmac_f32_e32 v69, v27, v31
	v_pk_mul_f32 v[22:23], v[92:93], v[22:23] op_sel_hi:[0,1]
	v_fmac_f32_e32 v69, v28, v32
	v_pk_fma_f32 v[26:27], v[88:89], v[90:91], v[22:23] op_sel_hi:[1,0,1]
	v_fmac_f32_e32 v69, v29, v33
	s_waitcnt lgkmcnt(0)
	v_pk_mul_f32 v[18:19], v[18:19], v[26:27]
	s_nop 0
	v_add_f32_e32 v18, v18, v69
	v_add_f32_e32 v22, v19, v18
	v_pk_mul_f32 v[18:19], v[92:93], v[24:25] op_sel_hi:[0,1]
	v_pk_fma_f32 v[28:29], v[96:97], v[90:91], v[18:19] op_sel_hi:[1,0,1]
	s_nop 0
	v_pk_mul_f32 v[18:19], v[20:21], v[28:29]
	s_nop 0
	v_add_f32_e32 v18, v18, v22
	v_add_f32_e32 v24, v19, v18
	ds_read_b128 v[18:21], v68 offset:4640
	v_pk_mul_f32 v[22:23], v[92:93], v[70:71] op_sel_hi:[0,1]
	v_pk_fma_f32 v[22:23], v[78:79], v[90:91], v[22:23] op_sel_hi:[1,0,1]
	s_waitcnt lgkmcnt(0)
	v_pk_mul_f32 v[18:19], v[18:19], v[22:23]
	s_nop 0
	v_add_f32_e32 v18, v18, v24
	v_add_f32_e32 v69, v19, v18
	v_pk_mul_f32 v[18:19], v[92:93], v[72:73] op_sel_hi:[0,1]
	v_pk_fma_f32 v[24:25], v[80:81], v[90:91], v[18:19] op_sel_hi:[1,0,1]
	ds_read_b128 v[70:73], v68 offset:4656
	v_pk_mul_f32 v[18:19], v[20:21], v[24:25]
	v_add_u32_e32 v68, 0x400, v68
	v_add_f32_e32 v18, v18, v69
	v_add_f32_e32 v69, v19, v18
	v_pk_mul_f32 v[18:19], v[92:93], v[74:75] op_sel_hi:[0,1]
	v_pk_fma_f32 v[18:19], v[82:83], v[90:91], v[18:19] op_sel_hi:[1,0,1]
	s_waitcnt lgkmcnt(0)
	v_pk_mul_f32 v[20:21], v[70:71], v[18:19]
	s_nop 0
	v_add_f32_e32 v20, v20, v69
	v_add_f32_e32 v69, v21, v20
	v_pk_mul_f32 v[20:21], v[92:93], v[76:77] op_sel_hi:[0,1]
	v_pk_fma_f32 v[20:21], v[84:85], v[90:91], v[20:21] op_sel_hi:[1,0,1]
	s_nop 0
	v_pk_mul_f32 v[70:71], v[72:73], v[20:21]
	s_nop 0
	v_add_f32_e32 v69, v70, v69
	v_add_f32_e32 v69, v71, v69
	ds_write_b32 v37, v69 offset:2048
	v_add_u32_e32 v37, 0x1000, v37
	s_cbranch_scc0 .LBB0_300
	s_waitcnt lgkmcnt(0)
	s_barrier
	v_add_u32_e32 v70, 64, v60
	s_waitcnt vmcnt(11)
	v_lshlrev_b32_e32 v37, 16, v44
	ds_read_b32 v44, v55 offset:8192
	ds_read2st64_b32 v[68:69], v70 offset0:40 offset1:41
	s_ashr_i32 s18, s33, 5
	s_ashr_i32 s19, s18, 31
	s_lshl_b32 s48, s25, 7
	s_waitcnt vmcnt(0) lgkmcnt(0)
	v_fma_f32 v44, v45, v44, v68
	v_add_f32_e32 v68, v44, v69
	ds_read2st64_b32 v[44:45], v70 offset0:42 offset1:43
	v_mul_f32_e32 v69, 0xbfb8aa3b, v37
	v_exp_f32_e32 v69, v69
	s_waitcnt lgkmcnt(0)
	v_add_f32_e32 v44, v68, v44
	v_add_f32_e32 v68, v44, v45
	ds_read2st64_b32 v[44:45], v70 offset0:44 offset1:45
	v_add_f32_e32 v69, 1.0, v69
	v_rcp_f32_e32 v69, v69
	s_waitcnt lgkmcnt(0)
	v_add_f32_e32 v44, v68, v44
	v_add_f32_e32 v68, v44, v45
	ds_read2st64_b32 v[44:45], v70 offset0:46 offset1:47
	v_mul_f32_e32 v37, v69, v37
	s_waitcnt lgkmcnt(0)
	v_add_f32_e32 v44, v68, v44
	v_add_f32_e32 v68, v44, v45
	v_lshl_add_u64 v[44:45], s[18:19], 3, v[40:41]
	v_mul_f32_e32 v70, v37, v68
	v_lshlrev_b64 v[68:69], 12, v[44:45]
	v_lshl_add_u64 v[68:69], s[74:75], 0, v[68:69]
	v_lshl_add_u64 v[68:69], v[68:69], 0, s[48:49]
	v_mov_b32_e32 v37, v1
	v_lshl_add_u64 v[68:69], v[68:69], 0, v[36:37]
	v_cvt_pk_bf16_f32 v71, v70, v70
	global_store_short v[68:69], v71, off
	v_and_b32_e32 v68, 64, v177
	v_add_u32_e32 v68, 64, v68
	v_xor_b32_e32 v69, 32, v177
	v_cmp_lt_i32_e32 vcc, v69, v68
	v_mul_f32_e32 v37, v70, v70
	s_nop 0
	v_cndmask_b32_e32 v69, v177, v69, vcc
	v_lshlrev_b32_e32 v69, 2, v69
	ds_bpermute_b32 v37, v69, v37
	v_xor_b32_e32 v69, 16, v177
	v_cmp_lt_i32_e32 vcc, v69, v68
	s_waitcnt lgkmcnt(0)
	v_fmac_f32_e32 v37, v70, v70
	v_cndmask_b32_e32 v69, v177, v69, vcc
	v_lshlrev_b32_e32 v69, 2, v69
	ds_bpermute_b32 v69, v69, v37
	s_waitcnt lgkmcnt(0)
	v_add_f32_e32 v37, v37, v69
	s_nop 1
	v_add_f32_dpp v37, v37, v37 row_ror:8 row_mask:0xf bank_mask:0xf
	s_nop 1
	v_add_f32_dpp v37, v37, v37 row_ror:4 row_mask:0xf bank_mask:0xf
	s_nop 1
	v_add_f32_dpp v37, v37, v37 quad_perm:[2,3,0,1] row_mask:0xf bank_mask:0xf
	s_nop 1
	v_add_f32_dpp v37, v37, v37 quad_perm:[1,0,3,2] row_mask:0xf bank_mask:0xf
	s_and_saveexec_b64 s[20:21], s[8:9]
	s_cbranch_execz .LBB0_291
	s_waitcnt lgkmcnt(0)
	v_mul_f32_e32 v37, 0x4b800000, v37
	v_trunc_f32_e32 v37, v37
	v_mul_f32_e32 v68, 0x2f800000, v37
	v_floor_f32_e32 v69, v68
	s_lshr_b32 s26, s25, 3
	v_fmac_f32_e32 v37, 0xcf800000, v69
	s_mul_i32 s26, s26, 0x22000
	v_cvt_u32_f32_e32 v68, v37
	v_cvt_u32_f32_e32 v69, v69
	s_add_u32 s26, s4, s26
	s_addc_u32 s27, s5, 0
	v_lshl_add_u64 v[44:45], v[44:45], 3, s[26:27]
	global_atomic_add_x2 v[44:45], v[68:69], off
	s_branch .LBB0_291
